# P4: skip the MFMAs of 64-row blocks lying entirely past the sequence end (last halo tile of each sequence)
# baseline (speedup 1.0000x reference)
; #define PG8_WAIT_V(n) asm volatile("s_waitcnt vmcnt(" #n ")" ::: "memory")
; #define PG8_BAR __builtin_amdgcn_s_barrier()
; __device__ __forceinline__ void halo_decode(int pm, int& seqbase, int& t0, int& slen) {
;     if (pm < NBATCH * HT_P) { const int s = pm / HT_P, j = pm - s * HT_P; seqbase = s * SP; t0 = 248 * j; slen = SP; }
;     else { const int q = pm - NBATCH * HT_P, s = q / HT_S, j = q - s * HT_S; seqbase = MP + s * SS; t0 = 248 * j; slen = SS; }
; }
; template <class Epi, bool HALO>
; __device__ __forceinline__ void gemm_phase(LAS unsigned char* lds, const bf16_t* Ag, const bf16_t* Btg, const int K, const int nM, const int nN, const int G, const int cidx, const int wave_, const Epi& E) {
;     ...
;     Unit cur, nxt; int ui = 0;
;     if (!S.next(0, cur)) return;
;     f32x4 acc[2][2][4][2];
; #pragma unroll
;     for (int a = 0; a < 2; ++a)
; #pragma unroll
;         for (int b = 0; b < 2; ++b)
; #pragma unroll
;             for (int m = 0; m < 4; ++m)
; #pragma unroll
;                 for (int n = 0; n < 2; ++n) acc[a][b][m][n] = (f32x4){0.f, 0.f, 0.f, 0.f};
;     bf16x8 At[4][2], B0[2][2], B1[2][2];
;     const char* cA = PG8_ABASE(cur.pm); const char* cB = PG8_BBASE(cur.pn);
;     PG8_STAGE(PG8_SB(0, 0), cB, voffB); PG8_STAGE(PG8_SB(0, 1), cB + hstepB, voffB); PG8_STAGE(PG8_SA(0, 0), cA, voffA); PG8_STAGE(PG8_SA(0, 1), cA + hstepA, voffA);
;     if (wr == 1) PG8_BAR;
;     PG8_WAIT_V(2); PG8_BAR;
;     PG8_STAGE(PG8_SB(1, 0), cB + kstep, voffB); PG8_STAGE(PG8_SA(1, 0), cA + kstep, voffA); PG8_STAGE(PG8_SB(1, 1), cB + hstepB + kstep, voffB);
;     PG8_WAIT_V(6); PG8_BAR;
;     for (;;) {
;         const bool has_next = S.next(ui + 1, nxt);
;         const char* nA = has_next ? PG8_ABASE(nxt.pm) : cA; const char* nB = has_next ? PG8_BBASE(nxt.pn) : cB;
;         for (int t = 0; t < nt; t += 2) {
;             const bool last = (t == nt - 2);
;             const char* a1 = cA + (size_t)(t + 1) * kstep;
;             const char* a2 = last ? nA : cA + (size_t)(t + 2) * kstep; const char* b2 = last ? nB : cB + (size_t)(t + 2) * kstep;
;             const char* a3 = a2 + kstep; const char* b3 = b2 + kstep;
;             PG8_LDB(B0, 0, 0); PG8_LDB(B1, 0, 1); PG8_SCHED; PG8_LDA(At, 0, 0); PG8_STAGE(PG8_SA(1, 1), a1 + hstepA, voffA);
;             PG8_WAIT_V(8); PG8_WAIT_L(0); PG8_BAR; PG8_MMA(0, 0, At, B0); PG8_MMA(0, 1, At, B1); PG8_BAR; PG8_SCHED;
.LBB0_786:
	s_cmpk_gt_i32 s36, 0x10f
	s_cbranch_scc1 HSK_smp
	s_mul_hi_i32 s86, s36, 0x78787879
	s_lshr_b32 s87, s86, 31
	s_ashr_i32 s86, s86, 4
	s_add_i32 s86, s86, s87
	s_mul_i32 s86, s86, 34
	s_sub_i32 s86, s36, s86
	s_movk_i32 s87, 0x2000
	s_branch HSK_join
HSK_smp:
	s_add_i32 s86, s36, 0xfffffef0
	s_mul_hi_u32 s87, s86, 0x38e38e39
	s_lshr_b32 s87, s87, 1
	s_mul_i32 s87, s87, 9
	s_sub_i32 s86, s86, s87
	s_movk_i32 s87, 0x800
HSK_join:
	s_mul_i32 s86, s86, 0xf8
	s_bfe_u32 s88, s81, 0x10008
	s_mul_i32 s88, s88, 62
	s_add_i32 s86, s86, s88
	s_add_i32 s86, s86, -1
	s_cmp_ge_i32 s86, s87
	s_cselect_b32 s91, 1, 0
	s_addk_i32 s86, 0x7c
	s_cmp_ge_i32 s86, s87
	s_cselect_b32 s92, 1, 0
	s_ashr_i32 s29, s28, 31
	s_lshl_b64 s[20:21], s[28:29], 19
	s_add_u32 s34, s38, s20
	s_addc_u32 s35, s39, s21
	s_and_b64 s[14:15], s[14:15], exec
	s_cselect_b32 s20, s35, s19
	s_cselect_b32 s21, s34, s18
	s_add_u32 s2, s2, 0x3e080
	s_addc_u32 s3, s3, 0
	s_add_u32 s29, s18, 0x100
	v_mov_b32_e32 v0, 0
	s_addc_u32 s37, s19, 0
	s_mov_b32 s51, -2
	v_mov_b32_e32 v1, v0
	v_mov_b32_e32 v2, v0
	v_mov_b32_e32 v3, v0
	v_mov_b32_e32 v32, v0
	v_mov_b32_e32 v33, v0
	v_mov_b32_e32 v34, v0
	v_mov_b32_e32 v35, v0
	v_mov_b32_e32 v4, v0
	v_mov_b32_e32 v5, v0
	v_mov_b32_e32 v6, v0
	v_mov_b32_e32 v7, v0
	v_mov_b32_e32 v36, v0
	v_mov_b32_e32 v37, v0
	v_mov_b32_e32 v38, v0
	v_mov_b32_e32 v39, v0
	v_mov_b32_e32 v8, v0
	v_mov_b32_e32 v9, v0
	v_mov_b32_e32 v10, v0
	v_mov_b32_e32 v11, v0
	v_mov_b32_e32 v40, v0
	v_mov_b32_e32 v41, v0
	v_mov_b32_e32 v42, v0
	v_mov_b32_e32 v43, v0
	v_mov_b32_e32 v12, v0
	v_mov_b32_e32 v13, v0
	v_mov_b32_e32 v14, v0
	v_mov_b32_e32 v15, v0
	v_mov_b32_e32 v44, v0
	v_mov_b32_e32 v45, v0
	v_mov_b32_e32 v46, v0
	v_mov_b32_e32 v47, v0
	v_mov_b32_e32 v16, v0
	v_mov_b32_e32 v17, v0
	v_mov_b32_e32 v18, v0
	v_mov_b32_e32 v19, v0
	v_mov_b32_e32 v48, v0
	v_mov_b32_e32 v49, v0
	v_mov_b32_e32 v50, v0
	v_mov_b32_e32 v51, v0
	v_mov_b32_e32 v20, v0
	v_mov_b32_e32 v21, v0
	v_mov_b32_e32 v22, v0
	v_mov_b32_e32 v23, v0
	v_mov_b32_e32 v52, v0
	v_mov_b32_e32 v53, v0
	v_mov_b32_e32 v54, v0
	v_mov_b32_e32 v55, v0
	v_mov_b32_e32 v24, v0
	v_mov_b32_e32 v25, v0
	v_mov_b32_e32 v26, v0
	v_mov_b32_e32 v27, v0
	v_mov_b32_e32 v56, v0
	v_mov_b32_e32 v57, v0
	v_mov_b32_e32 v58, v0
	v_mov_b32_e32 v59, v0
	v_mov_b32_e32 v28, v0
	v_mov_b32_e32 v29, v0
	v_mov_b32_e32 v30, v0
	v_mov_b32_e32 v31, v0
	v_mov_b32_e32 v60, v0
	v_mov_b32_e32 v61, v0
	v_mov_b32_e32 v62, v0
	v_mov_b32_e32 v63, v0
	v_mov_b32_e32 v64, v0
	v_mov_b32_e32 v65, v0
	v_mov_b32_e32 v66, v0
	v_mov_b32_e32 v67, v0
	v_mov_b32_e32 v96, v0
	v_mov_b32_e32 v97, v0
	v_mov_b32_e32 v98, v0
	v_mov_b32_e32 v99, v0
	v_mov_b32_e32 v68, v0
	v_mov_b32_e32 v69, v0
	v_mov_b32_e32 v70, v0
	v_mov_b32_e32 v71, v0
	v_mov_b32_e32 v100, v0
	v_mov_b32_e32 v101, v0
	v_mov_b32_e32 v102, v0
	v_mov_b32_e32 v103, v0
	v_mov_b32_e32 v72, v0
	v_mov_b32_e32 v73, v0
	v_mov_b32_e32 v74, v0
	v_mov_b32_e32 v75, v0
	v_mov_b32_e32 v104, v0
	v_mov_b32_e32 v105, v0
	v_mov_b32_e32 v106, v0
	v_mov_b32_e32 v107, v0
	v_mov_b32_e32 v76, v0
	v_mov_b32_e32 v77, v0
	v_mov_b32_e32 v78, v0
	v_mov_b32_e32 v79, v0
	v_mov_b32_e32 v108, v0
	v_mov_b32_e32 v109, v0
	v_mov_b32_e32 v110, v0
	v_mov_b32_e32 v111, v0
	v_mov_b32_e32 v80, v0
	v_mov_b32_e32 v81, v0
	v_mov_b32_e32 v82, v0
	v_mov_b32_e32 v83, v0
	v_mov_b32_e32 v112, v0
	v_mov_b32_e32 v113, v0
	v_mov_b32_e32 v114, v0
	v_mov_b32_e32 v115, v0
	v_mov_b32_e32 v84, v0
	v_mov_b32_e32 v85, v0
	v_mov_b32_e32 v86, v0
	v_mov_b32_e32 v87, v0
	v_mov_b32_e32 v116, v0
	v_mov_b32_e32 v117, v0
	v_mov_b32_e32 v118, v0
	v_mov_b32_e32 v119, v0
	v_mov_b32_e32 v88, v0
	v_mov_b32_e32 v89, v0
	v_mov_b32_e32 v90, v0
	v_mov_b32_e32 v91, v0
	v_mov_b32_e32 v120, v0
	v_mov_b32_e32 v121, v0
	v_mov_b32_e32 v122, v0
	v_mov_b32_e32 v123, v0
	v_mov_b32_e32 v92, v0
	v_mov_b32_e32 v93, v0
	v_mov_b32_e32 v94, v0
	v_mov_b32_e32 v95, v0
	v_mov_b32_e32 v124, v0
	v_mov_b32_e32 v125, v0
	v_mov_b32_e32 v126, v0
	v_mov_b32_e32 v127, v0
.LBB0_787:
	s_add_u32 s14, s2, 0xfffc2080
	s_addc_u32 s15, s3, -1
	s_add_i32 s52, 0, 0x10000
	s_cmp_eq_u32 s51, 12
	s_cselect_b32 s19, s31, s15
	s_cselect_b32 s18, s30, s14
	s_cselect_b32 s15, s20, s37
	s_cselect_b32 s14, s21, s29
	s_add_i32 s54, 0, 0x14000
	v_add_u32_e32 v140, s52, v185
	v_add_u32_e32 v144, s54, v185
	ds_read_b128 v[128:131], v140
	ds_read_b128 v[132:135], v140 offset:1024
	ds_read_b128 v[136:139], v140 offset:2048
	ds_read_b128 v[140:143], v140 offset:3072
	ds_read_b128 v[178:181], v144
	ds_read_b128 v[190:193], v144 offset:1024
	ds_read_b128 v[194:197], v144 offset:2048
	ds_read_b128 v[198:201], v144 offset:3072
	v_lshl_add_u64 v[170:171], s[2:3], 0, v[166:167]
	s_add_i32 m0, s41, 0xc000
	ds_read_b128 v[202:205], v189
	ds_read_b128 v[206:209], v189 offset:1024
	ds_read_b128 v[210:213], v189 offset:2048
	ds_read_b128 v[214:217], v189 offset:3072
	ds_read_b128 v[218:221], v189 offset:4096
	ds_read_b128 v[222:225], v189 offset:5120
	ds_read_b128 v[226:229], v189 offset:6144
	ds_read_b128 v[230:233], v189 offset:7168
	global_load_lds_dwordx4 v[170:171], off
	v_lshl_add_u64 v[170:171], s[2:3], 0, v[168:169]
	s_add_i32 m0, s41, 0xe000
	s_nop 0
	global_load_lds_dwordx4 v[170:171], off
	s_waitcnt vmcnt(8)
	s_waitcnt lgkmcnt(0)
	s_barrier
	s_setprio 1
	s_waitcnt lgkmcnt(0)
	s_cmp_lg_u32 s91, 0
	s_cbranch_scc1 HSK_skip0
; #define PG8_STAGE(bufoff, gbase, voff) do { _Pragma("unroll") for (int _i = 0; _i < 2; ++_i) \
;         __builtin_amdgcn_global_load_lds((const unsigned*)((const char*)(gbase) + (voff)[_i]), (LAS unsigned*)(lds + (bufoff) + ldsw + _i * 8192), 16, 0, 0); } while (0)
; #define PG8_LDA(dst, b, h) do { _Pragma("unroll") for (int m = 0; m < 4; ++m) _Pragma("unroll") for (int k = 0; k < 2; ++k) dst[m][k] = *(const LAS bf16x8*)(lds + PG8_SA(b, h) + aoff + m * 2048 + k * 1024); } while (0)
; #define PG8_MMA(ai, bj, At, Bt) do { __builtin_amdgcn_s_setprio(1); _Pragma("unroll") for (int m = 0; m < 4; ++m) _Pragma("unroll") for (int n = 0; n < 2; ++n) _Pragma("unroll") for (int k = 0; k < 2; ++k) \
;         acc[ai][bj][m][n] = __builtin_amdgcn_mfma_f32_16x16x32_bf16(Bt[n][k], At[m][k], acc[ai][bj][m][n], 0, 0, 0); __builtin_amdgcn_s_setprio(0); } while (0)
; #define PG8_WAIT_V(n) asm volatile("s_waitcnt vmcnt(" #n ")" ::: "memory")
; #define PG8_WAIT_L(n) asm volatile("s_waitcnt lgkmcnt(" #n ")" ::: "memory")
; #define PG8_BAR __builtin_amdgcn_s_barrier()
; #define PG8_SCHED __builtin_amdgcn_sched_barrier(0)
; template <class Epi, bool HALO>
; __device__ __forceinline__ void gemm_phase(LAS unsigned char* lds, const bf16_t* Ag, const bf16_t* Btg, const int K, const int nM, const int nN, const int G, const int cidx, const int wave_, const Epi& E) {
;     ...
;             PG8_WAIT_V(8); PG8_WAIT_L(0); PG8_BAR; PG8_MMA(0, 0, At, B0); PG8_MMA(0, 1, At, B1); PG8_BAR; PG8_SCHED;
;             PG8_LDA(At, 0, 1); PG8_STAGE(PG8_SB(0, 0), b2, voffB); PG8_STAGE(PG8_SB(0, 1), b2 + hstepB, voffB); PG8_STAGE(PG8_SA(0, 0), a2, voffA);
;             PG8_WAIT_V(8); PG8_WAIT_L(0); PG8_BAR; PG8_MMA(1, 0, At, B0); PG8_MMA(1, 1, At, B1); PG8_BAR; PG8_SCHED;
	v_mfma_f32_16x16x32_bf16 v[124:127], v[128:131], v[202:205], v[124:127]
	v_mfma_f32_16x16x32_bf16 v[92:95], v[136:139], v[202:205], v[92:95]
	v_mfma_f32_16x16x32_bf16 v[120:123], v[128:131], v[210:213], v[120:123]
	v_mfma_f32_16x16x32_bf16 v[88:91], v[136:139], v[210:213], v[88:91]
	v_mfma_f32_16x16x32_bf16 v[116:119], v[128:131], v[218:221], v[116:119]
	v_mfma_f32_16x16x32_bf16 v[84:87], v[136:139], v[218:221], v[84:87]
	v_mfma_f32_16x16x32_bf16 v[112:115], v[128:131], v[226:229], v[112:115]
	v_mfma_f32_16x16x32_bf16 v[80:83], v[136:139], v[226:229], v[80:83]
	v_mfma_f32_16x16x32_bf16 v[124:127], v[132:135], v[206:209], v[124:127]
	v_mfma_f32_16x16x32_bf16 v[92:95], v[140:143], v[206:209], v[92:95]
	v_mfma_f32_16x16x32_bf16 v[120:123], v[132:135], v[214:217], v[120:123]
	v_mfma_f32_16x16x32_bf16 v[88:91], v[140:143], v[214:217], v[88:91]
	v_mfma_f32_16x16x32_bf16 v[116:119], v[132:135], v[222:225], v[116:119]
	v_mfma_f32_16x16x32_bf16 v[84:87], v[140:143], v[222:225], v[84:87]
	v_mfma_f32_16x16x32_bf16 v[112:115], v[132:135], v[230:233], v[112:115]
	v_mfma_f32_16x16x32_bf16 v[80:83], v[140:143], v[230:233], v[80:83]
	s_setprio 0
	s_setprio 1
	v_mfma_f32_16x16x32_bf16 v[108:111], v[178:181], v[202:205], v[108:111]
	v_mfma_f32_16x16x32_bf16 v[76:79], v[194:197], v[202:205], v[76:79]
	v_mfma_f32_16x16x32_bf16 v[104:107], v[178:181], v[210:213], v[104:107]
	v_mfma_f32_16x16x32_bf16 v[72:75], v[194:197], v[210:213], v[72:75]
	v_mfma_f32_16x16x32_bf16 v[100:103], v[178:181], v[218:221], v[100:103]
	v_mfma_f32_16x16x32_bf16 v[68:71], v[194:197], v[218:221], v[68:71]
	v_mfma_f32_16x16x32_bf16 v[96:99], v[178:181], v[226:229], v[96:99]
	v_mfma_f32_16x16x32_bf16 v[64:67], v[194:197], v[226:229], v[64:67]
	v_mfma_f32_16x16x32_bf16 v[108:111], v[190:193], v[206:209], v[108:111]
	v_mfma_f32_16x16x32_bf16 v[76:79], v[198:201], v[206:209], v[76:79]
	v_mfma_f32_16x16x32_bf16 v[104:107], v[190:193], v[214:217], v[104:107]
	v_mfma_f32_16x16x32_bf16 v[72:75], v[198:201], v[214:217], v[72:75]
	v_mfma_f32_16x16x32_bf16 v[100:103], v[190:193], v[222:225], v[100:103]
	v_mfma_f32_16x16x32_bf16 v[68:71], v[198:201], v[222:225], v[68:71]
	v_mfma_f32_16x16x32_bf16 v[96:99], v[190:193], v[230:233], v[96:99]
	v_mfma_f32_16x16x32_bf16 v[64:67], v[198:201], v[230:233], v[64:67]
HSK_skip0:
	s_setprio 0
	s_barrier
	s_add_i32 s52, s52, s40
	v_lshl_add_u64 v[170:171], s[14:15], 0, v[156:157]
	s_mov_b32 m0, s52
	ds_read_b128 v[202:205], v189 offset:16384
	ds_read_b128 v[206:209], v189 offset:17408
	ds_read_b128 v[210:213], v189 offset:18432
	ds_read_b128 v[214:217], v189 offset:19456
	ds_read_b128 v[218:221], v189 offset:20480
	ds_read_b128 v[222:225], v189 offset:21504
	ds_read_b128 v[226:229], v189 offset:22528
	ds_read_b128 v[230:233], v189 offset:23552
	global_load_lds_dwordx4 v[170:171], off
	s_add_i32 m0, s52, 0x2000
	s_add_u32 s52, s14, 0x40000
	v_lshl_add_u64 v[182:183], s[14:15], 0, v[152:153]
	s_addc_u32 s53, s15, 0
	s_add_i32 s54, s54, s40
	global_load_lds_dwordx4 v[182:183], off
	v_lshl_add_u64 v[234:235], s[52:53], 0, v[156:157]
	s_mov_b32 m0, s54
	v_lshl_add_u64 v[236:237], s[18:19], 0, v[154:155]
	global_load_lds_dwordx4 v[234:235], off
	v_lshl_add_u64 v[234:235], s[52:53], 0, v[152:153]
	s_add_i32 m0, s54, 0x2000
	s_nop 0
	global_load_lds_dwordx4 v[234:235], off
	v_lshl_add_u64 v[234:235], s[18:19], 0, v[158:159]
	s_mov_b32 m0, s41
	s_nop 0
	global_load_lds_dwordx4 v[234:235], off
	s_mov_b32 m0, s42
	s_nop 0
	global_load_lds_dwordx4 v[236:237], off
	s_waitcnt vmcnt(8)
	s_waitcnt lgkmcnt(0)
	s_barrier
	s_setprio 1
	s_waitcnt lgkmcnt(0)
	s_cmp_lg_u32 s92, 0
	s_cbranch_scc1 HSK_skip1
	v_mfma_f32_16x16x32_bf16 v[60:63], v[128:131], v[202:205], v[60:63]
	v_mfma_f32_16x16x32_bf16 v[28:31], v[136:139], v[202:205], v[28:31]
	v_mfma_f32_16x16x32_bf16 v[56:59], v[128:131], v[210:213], v[56:59]
	v_mfma_f32_16x16x32_bf16 v[24:27], v[136:139], v[210:213], v[24:27]
	v_mfma_f32_16x16x32_bf16 v[52:55], v[128:131], v[218:221], v[52:55]
	v_mfma_f32_16x16x32_bf16 v[20:23], v[136:139], v[218:221], v[20:23]
	v_mfma_f32_16x16x32_bf16 v[48:51], v[128:131], v[226:229], v[48:51]
	v_mfma_f32_16x16x32_bf16 v[16:19], v[136:139], v[226:229], v[16:19]
	v_mfma_f32_16x16x32_bf16 v[60:63], v[132:135], v[206:209], v[60:63]
	v_mfma_f32_16x16x32_bf16 v[28:31], v[140:143], v[206:209], v[28:31]
	v_mfma_f32_16x16x32_bf16 v[56:59], v[132:135], v[214:217], v[56:59]
	v_mfma_f32_16x16x32_bf16 v[24:27], v[140:143], v[214:217], v[24:27]
	v_mfma_f32_16x16x32_bf16 v[52:55], v[132:135], v[222:225], v[52:55]
	v_mfma_f32_16x16x32_bf16 v[20:23], v[140:143], v[222:225], v[20:23]
	v_mfma_f32_16x16x32_bf16 v[48:51], v[132:135], v[230:233], v[48:51]
	v_mfma_f32_16x16x32_bf16 v[16:19], v[140:143], v[230:233], v[16:19]
	s_setprio 0
	s_setprio 1
	v_mfma_f32_16x16x32_bf16 v[44:47], v[178:181], v[202:205], v[44:47]
	v_mfma_f32_16x16x32_bf16 v[12:15], v[194:197], v[202:205], v[12:15]
	v_mfma_f32_16x16x32_bf16 v[40:43], v[178:181], v[210:213], v[40:43]
	v_mfma_f32_16x16x32_bf16 v[8:11], v[194:197], v[210:213], v[8:11]
	v_mfma_f32_16x16x32_bf16 v[36:39], v[178:181], v[218:221], v[36:39]
	v_mfma_f32_16x16x32_bf16 v[4:7], v[194:197], v[218:221], v[4:7]
	v_mfma_f32_16x16x32_bf16 v[32:35], v[178:181], v[226:229], v[32:35]
	v_mfma_f32_16x16x32_bf16 v[0:3], v[194:197], v[226:229], v[0:3]
	v_mfma_f32_16x16x32_bf16 v[44:47], v[190:193], v[206:209], v[44:47]
	v_mfma_f32_16x16x32_bf16 v[12:15], v[198:201], v[206:209], v[12:15]
	v_mfma_f32_16x16x32_bf16 v[40:43], v[190:193], v[214:217], v[40:43]
	v_mfma_f32_16x16x32_bf16 v[8:11], v[198:201], v[214:217], v[8:11]
	v_mfma_f32_16x16x32_bf16 v[36:39], v[190:193], v[222:225], v[36:39]
	v_mfma_f32_16x16x32_bf16 v[4:7], v[198:201], v[222:225], v[4:7]
	v_mfma_f32_16x16x32_bf16 v[32:35], v[190:193], v[230:233], v[32:35]
	v_mfma_f32_16x16x32_bf16 v[0:3], v[198:201], v[230:233], v[0:3]
; #define PG8_STAGE(bufoff, gbase, voff) do { _Pragma("unroll") for (int _i = 0; _i < 2; ++_i) \
;         __builtin_amdgcn_global_load_lds((const unsigned*)((const char*)(gbase) + (voff)[_i]), (LAS unsigned*)(lds + (bufoff) + ldsw + _i * 8192), 16, 0, 0); } while (0)
; #define PG8_LDA(dst, b, h) do { _Pragma("unroll") for (int m = 0; m < 4; ++m) _Pragma("unroll") for (int k = 0; k < 2; ++k) dst[m][k] = *(const LAS bf16x8*)(lds + PG8_SA(b, h) + aoff + m * 2048 + k * 1024); } while (0)
; #define PG8_LDB(dst, b, h) do { _Pragma("unroll") for (int n = 0; n < 2; ++n) _Pragma("unroll") for (int k = 0; k < 2; ++k) dst[n][k] = *(const LAS bf16x8*)(lds + PG8_SB(b, h) + boff + n * 2048 + k * 1024); } while (0)
; #define PG8_MMA(ai, bj, At, Bt) do { __builtin_amdgcn_s_setprio(1); _Pragma("unroll") for (int m = 0; m < 4; ++m) _Pragma("unroll") for (int n = 0; n < 2; ++n) _Pragma("unroll") for (int k = 0; k < 2; ++k) \
;         acc[ai][bj][m][n] = __builtin_amdgcn_mfma_f32_16x16x32_bf16(Bt[n][k], At[m][k], acc[ai][bj][m][n], 0, 0, 0); __builtin_amdgcn_s_setprio(0); } while (0)
; #define PG8_WAIT_V(n) asm volatile("s_waitcnt vmcnt(" #n ")" ::: "memory")
; #define PG8_WAIT_L(n) asm volatile("s_waitcnt lgkmcnt(" #n ")" ::: "memory")
; #define PG8_BAR __builtin_amdgcn_s_barrier()
; #define PG8_SCHED __builtin_amdgcn_sched_barrier(0)
; template <class Epi, bool HALO>
; __device__ __forceinline__ void gemm_phase(LAS unsigned char* lds, const bf16_t* Ag, const bf16_t* Btg, const int K, const int nM, const int nN, const int G, const int cidx, const int wave_, const Epi& E) {
;     ...
;             PG8_LDB(B0, 1, 0); PG8_LDB(B1, 1, 1); PG8_SCHED; PG8_LDA(At, 1, 0); PG8_STAGE(PG8_SA(0, 1), a2 + hstepA, voffA);
;             PG8_WAIT_V(8); PG8_WAIT_L(0); PG8_BAR; PG8_MMA(0, 0, At, B0); PG8_MMA(0, 1, At, B1); PG8_BAR; PG8_SCHED;
HSK_skip1:
	s_setprio 0
	s_barrier
	s_add_i32 s52, 0, 0x18000
	v_add_u32_e32 v140, s52, v185
	v_add_u32_e32 v144, s90, v185
	ds_read_b128 v[128:131], v140
	ds_read_b128 v[132:135], v140 offset:1024
	ds_read_b128 v[136:139], v140 offset:2048
	ds_read_b128 v[140:143], v140 offset:3072
	ds_read_b128 v[178:181], v144
	ds_read_b128 v[190:193], v144 offset:1024
	ds_read_b128 v[194:197], v144 offset:2048
	ds_read_b128 v[198:201], v144 offset:3072
	s_add_u32 s18, s18, 0x3e000
	s_addc_u32 s19, s19, 0
	s_mov_b32 m0, s43
	v_lshl_add_u64 v[238:239], s[18:19], 0, v[158:159]
	ds_read_b128 v[202:205], v189 offset:32768
	ds_read_b128 v[206:209], v189 offset:33792
	ds_read_b128 v[210:213], v189 offset:34816
	ds_read_b128 v[214:217], v189 offset:35840
	ds_read_b128 v[218:221], v189 offset:36864
	ds_read_b128 v[222:225], v189 offset:37888
	ds_read_b128 v[226:229], v189 offset:38912
	ds_read_b128 v[230:233], v189 offset:39936
	global_load_lds_dwordx4 v[238:239], off
	v_lshl_add_u64 v[238:239], s[18:19], 0, v[154:155]
	s_mov_b32 m0, s44
	s_nop 0
	global_load_lds_dwordx4 v[238:239], off
	s_waitcnt vmcnt(8)
	s_waitcnt lgkmcnt(0)
	s_barrier
	s_setprio 1
	s_waitcnt lgkmcnt(0)
	s_cmp_lg_u32 s91, 0
	s_cbranch_scc1 HSK_skip2
	v_mfma_f32_16x16x32_bf16 v[124:127], v[128:131], v[202:205], v[124:127]
	v_mfma_f32_16x16x32_bf16 v[92:95], v[136:139], v[202:205], v[92:95]
	v_mfma_f32_16x16x32_bf16 v[120:123], v[128:131], v[210:213], v[120:123]
	v_mfma_f32_16x16x32_bf16 v[88:91], v[136:139], v[210:213], v[88:91]
	v_mfma_f32_16x16x32_bf16 v[116:119], v[128:131], v[218:221], v[116:119]
	v_mfma_f32_16x16x32_bf16 v[84:87], v[136:139], v[218:221], v[84:87]
	v_mfma_f32_16x16x32_bf16 v[112:115], v[128:131], v[226:229], v[112:115]
	v_mfma_f32_16x16x32_bf16 v[80:83], v[136:139], v[226:229], v[80:83]
	v_mfma_f32_16x16x32_bf16 v[124:127], v[132:135], v[206:209], v[124:127]
	v_mfma_f32_16x16x32_bf16 v[92:95], v[140:143], v[206:209], v[92:95]
	v_mfma_f32_16x16x32_bf16 v[120:123], v[132:135], v[214:217], v[120:123]
	v_mfma_f32_16x16x32_bf16 v[88:91], v[140:143], v[214:217], v[88:91]
	v_mfma_f32_16x16x32_bf16 v[116:119], v[132:135], v[222:225], v[116:119]
	v_mfma_f32_16x16x32_bf16 v[84:87], v[140:143], v[222:225], v[84:87]
	v_mfma_f32_16x16x32_bf16 v[112:115], v[132:135], v[230:233], v[112:115]
	v_mfma_f32_16x16x32_bf16 v[80:83], v[140:143], v[230:233], v[80:83]
	s_setprio 0
	s_setprio 1
	v_mfma_f32_16x16x32_bf16 v[108:111], v[178:181], v[202:205], v[108:111]
	v_mfma_f32_16x16x32_bf16 v[76:79], v[194:197], v[202:205], v[76:79]
	v_mfma_f32_16x16x32_bf16 v[104:107], v[178:181], v[210:213], v[104:107]
	v_mfma_f32_16x16x32_bf16 v[72:75], v[194:197], v[210:213], v[72:75]
	v_mfma_f32_16x16x32_bf16 v[100:103], v[178:181], v[218:221], v[100:103]
	v_mfma_f32_16x16x32_bf16 v[68:71], v[194:197], v[218:221], v[68:71]
	v_mfma_f32_16x16x32_bf16 v[96:99], v[178:181], v[226:229], v[96:99]
	v_mfma_f32_16x16x32_bf16 v[64:67], v[194:197], v[226:229], v[64:67]
	v_mfma_f32_16x16x32_bf16 v[108:111], v[190:193], v[206:209], v[108:111]
	v_mfma_f32_16x16x32_bf16 v[76:79], v[198:201], v[206:209], v[76:79]
	v_mfma_f32_16x16x32_bf16 v[104:107], v[190:193], v[214:217], v[104:107]
	v_mfma_f32_16x16x32_bf16 v[72:75], v[198:201], v[214:217], v[72:75]
	v_mfma_f32_16x16x32_bf16 v[100:103], v[190:193], v[222:225], v[100:103]
	v_mfma_f32_16x16x32_bf16 v[68:71], v[198:201], v[222:225], v[68:71]
	v_mfma_f32_16x16x32_bf16 v[96:99], v[190:193], v[230:233], v[96:99]
	v_mfma_f32_16x16x32_bf16 v[64:67], v[198:201], v[230:233], v[64:67]
; #define PG8_STAGE(bufoff, gbase, voff) do { _Pragma("unroll") for (int _i = 0; _i < 2; ++_i) \
;         __builtin_amdgcn_global_load_lds((const unsigned*)((const char*)(gbase) + (voff)[_i]), (LAS unsigned*)(lds + (bufoff) + ldsw + _i * 8192), 16, 0, 0); } while (0)
; #define PG8_LDA(dst, b, h) do { _Pragma("unroll") for (int m = 0; m < 4; ++m) _Pragma("unroll") for (int k = 0; k < 2; ++k) dst[m][k] = *(const LAS bf16x8*)(lds + PG8_SA(b, h) + aoff + m * 2048 + k * 1024); } while (0)
; #define PG8_MMA(ai, bj, At, Bt) do { __builtin_amdgcn_s_setprio(1); _Pragma("unroll") for (int m = 0; m < 4; ++m) _Pragma("unroll") for (int n = 0; n < 2; ++n) _Pragma("unroll") for (int k = 0; k < 2; ++k) \
;         acc[ai][bj][m][n] = __builtin_amdgcn_mfma_f32_16x16x32_bf16(Bt[n][k], At[m][k], acc[ai][bj][m][n], 0, 0, 0); __builtin_amdgcn_s_setprio(0); } while (0)
; #define PG8_WAIT_V(n) asm volatile("s_waitcnt vmcnt(" #n ")" ::: "memory")
; #define PG8_WAIT_L(n) asm volatile("s_waitcnt lgkmcnt(" #n ")" ::: "memory")
; #define PG8_BAR __builtin_amdgcn_s_barrier()
; #define PG8_SCHED __builtin_amdgcn_sched_barrier(0)
; template <class Epi, bool HALO>
; __device__ __forceinline__ void gemm_phase(LAS unsigned char* lds, const bf16_t* Ag, const bf16_t* Btg, const int K, const int nM, const int nN, const int G, const int cidx, const int wave_, const Epi& E) {
;     ...
;             PG8_LDA(At, 1, 1); PG8_STAGE(PG8_SB(1, 0), b3, voffB); PG8_STAGE(PG8_SB(1, 1), b3 + hstepB, voffB); PG8_STAGE(PG8_SA(1, 0), a3, voffA);
;             PG8_WAIT_V(8); PG8_WAIT_L(0); PG8_BAR; PG8_MMA(1, 0, At, B0); PG8_MMA(1, 1, At, B1); PG8_BAR; PG8_SCHED;
;         }
;         if (wr == 0) PG8_BAR;
HSK_skip2:
	s_setprio 0
	s_barrier
	s_add_i32 s18, s52, s40
	v_lshl_add_u64 v[170:171], v[170:171], 0, s[94:95]
	s_mov_b32 m0, s18
	ds_read_b128 v[202:205], v189 offset:49152
	ds_read_b128 v[206:209], v189 offset:50176
	ds_read_b128 v[210:213], v189 offset:51200
	ds_read_b128 v[214:217], v189 offset:52224
	ds_read_b128 v[218:221], v189 offset:53248
	ds_read_b128 v[222:225], v189 offset:54272
	ds_read_b128 v[226:229], v189 offset:55296
	ds_read_b128 v[230:233], v189 offset:56320
	global_load_lds_dwordx4 v[170:171], off
	s_add_i32 m0, s18, 0x2000
	s_add_u32 s14, s14, 0x40080
	v_lshl_add_u64 v[170:171], v[182:183], 0, s[94:95]
	s_addc_u32 s15, s15, 0
	s_add_i32 s18, s90, s40
	global_load_lds_dwordx4 v[170:171], off
	v_lshl_add_u64 v[170:171], s[14:15], 0, v[156:157]
	s_mov_b32 m0, s18
	s_nop 0
	global_load_lds_dwordx4 v[170:171], off
	v_lshl_add_u64 v[170:171], s[14:15], 0, v[152:153]
	s_add_i32 m0, s18, 0x2000
	s_nop 0
	global_load_lds_dwordx4 v[170:171], off
	v_lshl_add_u64 v[170:171], v[234:235], 0, s[94:95]
	s_mov_b32 m0, s46
	s_nop 0
	global_load_lds_dwordx4 v[170:171], off
	v_lshl_add_u64 v[170:171], v[236:237], 0, s[94:95]
	s_mov_b32 m0, s47
	s_nop 0
	global_load_lds_dwordx4 v[170:171], off
	s_waitcnt vmcnt(8)
	s_waitcnt lgkmcnt(0)
	s_barrier
	s_setprio 1
	s_waitcnt lgkmcnt(0)
	s_cmp_lg_u32 s92, 0
	s_cbranch_scc1 HSK_skip3
	v_mfma_f32_16x16x32_bf16 v[60:63], v[128:131], v[202:205], v[60:63]
	v_mfma_f32_16x16x32_bf16 v[28:31], v[136:139], v[202:205], v[28:31]
	v_mfma_f32_16x16x32_bf16 v[56:59], v[128:131], v[210:213], v[56:59]
	v_mfma_f32_16x16x32_bf16 v[24:27], v[136:139], v[210:213], v[24:27]
	v_mfma_f32_16x16x32_bf16 v[52:55], v[128:131], v[218:221], v[52:55]
	v_mfma_f32_16x16x32_bf16 v[20:23], v[136:139], v[218:221], v[20:23]
	v_mfma_f32_16x16x32_bf16 v[48:51], v[128:131], v[226:229], v[48:51]
	v_mfma_f32_16x16x32_bf16 v[16:19], v[136:139], v[226:229], v[16:19]
	v_mfma_f32_16x16x32_bf16 v[60:63], v[132:135], v[206:209], v[60:63]
	v_mfma_f32_16x16x32_bf16 v[28:31], v[140:143], v[206:209], v[28:31]
	v_mfma_f32_16x16x32_bf16 v[56:59], v[132:135], v[214:217], v[56:59]
	v_mfma_f32_16x16x32_bf16 v[24:27], v[140:143], v[214:217], v[24:27]
	v_mfma_f32_16x16x32_bf16 v[52:55], v[132:135], v[222:225], v[52:55]
	v_mfma_f32_16x16x32_bf16 v[20:23], v[140:143], v[222:225], v[20:23]
	v_mfma_f32_16x16x32_bf16 v[48:51], v[132:135], v[230:233], v[48:51]
	v_mfma_f32_16x16x32_bf16 v[16:19], v[140:143], v[230:233], v[16:19]
	s_setprio 0
	s_setprio 1
	v_mfma_f32_16x16x32_bf16 v[44:47], v[178:181], v[202:205], v[44:47]
	v_mfma_f32_16x16x32_bf16 v[12:15], v[194:197], v[202:205], v[12:15]
	v_mfma_f32_16x16x32_bf16 v[40:43], v[178:181], v[210:213], v[40:43]
	v_mfma_f32_16x16x32_bf16 v[8:11], v[194:197], v[210:213], v[8:11]
	v_mfma_f32_16x16x32_bf16 v[36:39], v[178:181], v[218:221], v[36:39]
	v_mfma_f32_16x16x32_bf16 v[4:7], v[194:197], v[218:221], v[4:7]
	v_mfma_f32_16x16x32_bf16 v[32:35], v[178:181], v[226:229], v[32:35]
	v_mfma_f32_16x16x32_bf16 v[0:3], v[194:197], v[226:229], v[0:3]
	v_mfma_f32_16x16x32_bf16 v[44:47], v[190:193], v[206:209], v[44:47]
	v_mfma_f32_16x16x32_bf16 v[12:15], v[198:201], v[206:209], v[12:15]
	v_mfma_f32_16x16x32_bf16 v[40:43], v[190:193], v[214:217], v[40:43]
	v_mfma_f32_16x16x32_bf16 v[8:11], v[198:201], v[214:217], v[8:11]
	v_mfma_f32_16x16x32_bf16 v[36:39], v[190:193], v[222:225], v[36:39]
	v_mfma_f32_16x16x32_bf16 v[4:7], v[198:201], v[222:225], v[4:7]
	v_mfma_f32_16x16x32_bf16 v[32:35], v[190:193], v[230:233], v[32:35]
	v_mfma_f32_16x16x32_bf16 v[0:3], v[198:201], v[230:233], v[0:3]
HSK_skip3:
	s_setprio 0
	s_barrier
	s_add_i32 s51, s51, 2
	s_add_u32 s2, s2, 0x100
	s_addc_u32 s3, s3, 0
	s_add_u32 s29, s29, 0x100
	s_addc_u32 s37, s37, 0
	s_cmp_gt_u32 s51, 13
	s_cbranch_scc0 .LBB0_787
	s_and_b64 vcc, exec, s[26:27]
	s_cbranch_vccz .LBB0_790
	s_barrier
